# barrier-poll back-off: s_sleep 1 -> s_sleep 4 in all 34 grid-barrier spin loops, on top of v12
# speedup vs baseline: 1.0067x; 1.0032x over previous
; __global__ void __launch_bounds__(NT, 2) fwd_megakernel(Params p) {
;     ...
;     grid.sync();
.LBB0_252:
	s_sleep 4
	global_load_dword v2, v0, s[2:3] offset:32 sc1
	s_waitcnt vmcnt(0)
	v_and_b32_e32 v2, 0xffff0000, v2
	v_cmp_ne_u32_e32 vcc, v2, v1
	s_or_b64 s[6:7], vcc, s[6:7]
	s_andn2_b64 exec, exec, s[6:7]
	s_cbranch_execnz .LBB0_252

; __device__ __forceinline__ unsigned xb_ld(unsigned* p)              { return __hip_atomic_load(p, __ATOMIC_RELAXED, __HIP_MEMORY_SCOPE_AGENT); }
; __device__ __forceinline__ void xcd_barrier_complete(unsigned* bar, unsigned x, unsigned& nloc, unsigned& nx) {
;     const unsigned G = gridDim.x * gridDim.y * gridDim.z;
;     unsigned sum, cnt, mine, sp = 0u;
;     for (;;) {
;         sum = 0u; cnt = 0u; mine = 0u;
; #pragma unroll
;         for (unsigned j = 0; j < 16; ++j) { const unsigned c = xb_ld(&bar[XB_XCNT(j)]); sum += c; cnt += (c > 0u) ? 1u : 0u; mine = (j == x) ? c : mine; }
;         if (sum == G) break;
;         __builtin_amdgcn_s_sleep(1);
;         if ((++sp & 255u) == 0u) { if (xb_ld(&bar[XB_TMO])) break; if (sp > XB_SPIN_CAP) { atomicAdd(&bar[XB_TMO], 1u); break; } }
;     }
.LBB0_266:
	flat_load_dword v25, v[0:1] offset:1024 sc1
	flat_load_dword v10, v[0:1] offset:1280 sc1
	flat_load_dword v11, v[0:1] offset:1536 sc1
	flat_load_dword v12, v[0:1] offset:1792 sc1
	flat_load_dword v13, v[0:1] offset:2048 sc1
	flat_load_dword v14, v[0:1] offset:2304 sc1
	flat_load_dword v15, v[0:1] offset:2560 sc1
	flat_load_dword v16, v[0:1] offset:2816 sc1
	flat_load_dword v17, v[0:1] offset:3072 sc1
	flat_load_dword v18, v[0:1] offset:3328 sc1
	flat_load_dword v19, v[0:1] offset:3584 sc1
	flat_load_dword v20, v[0:1] offset:3840 sc1
	flat_load_dword v21, v[2:3] sc1
	flat_load_dword v22, v[4:5] sc1
	flat_load_dword v23, v[6:7] sc1
	flat_load_dword v24, v[8:9] sc1
	s_or_b64 s[8:9], s[8:9], exec
	s_or_b64 s[6:7], s[6:7], exec
	s_waitcnt vmcnt(0) lgkmcnt(0)
	v_add_u32_e32 v26, v10, v25
	v_add_u32_e32 v26, v26, v11
	v_add_u32_e32 v26, v26, v12
	v_add_u32_e32 v26, v26, v13
	v_add_u32_e32 v26, v26, v14
	v_add_u32_e32 v26, v26, v15
	v_add_u32_e32 v26, v26, v16
	v_add_u32_e32 v26, v26, v17
	v_add_u32_e32 v26, v26, v18
	v_add_u32_e32 v26, v26, v19
	v_add_u32_e32 v26, v26, v20
	v_add_u32_e32 v26, v26, v21
	v_add_u32_e32 v26, v26, v22
	v_add_u32_e32 v26, v26, v23
	v_add_u32_e32 v26, v26, v24
	v_cmp_ne_u32_e32 vcc, s20, v26
	s_and_saveexec_b64 s[10:11], vcc
	s_cbranch_execz .LBB0_265
	s_and_b32 s14, s21, 0xff
	s_mov_b64 s[12:13], -1
	s_cmp_eq_u32 s14, 0
	s_mov_b64 s[16:17], -1
	s_mov_b64 s[14:15], -1
	s_sleep 4
	s_cbranch_scc1 .LBB0_269
	s_and_saveexec_b64 s[18:19], s[16:17]
	s_cbranch_execz .LBB0_264
	s_branch .LBB0_272

.LBB0_280:
	s_and_b32 s16, s24, 0xff
	s_mov_b64 s[14:15], -1
	s_cmp_lg_u32 s16, 0
	s_mov_b64 s[16:17], -1
	s_sleep 4
	s_cbranch_scc1 .LBB0_284
	v_mov_b64_e32 v[2:3], s[34:35]
	flat_load_dword v0, v[2:3] offset:512 sc1
	s_mov_b64 s[16:17], 0
	s_mov_b64 s[18:19], -1
	s_waitcnt vmcnt(0) lgkmcnt(0)
	v_cmp_eq_u32_e32 vcc, 0, v0
	s_and_saveexec_b64 s[20:21], vcc
	s_cmp_lt_u32 s24, 0x40001
	s_cselect_b64 s[16:17], -1, 0
	s_xor_b64 s[18:19], exec, -1
	s_and_b64 s[16:17], s[16:17], exec
	s_or_b64 exec, exec, s[20:21]

.LBB0_294:
	s_and_b32 s14, s24, 0xff
	s_cmp_lg_u32 s14, 0
	s_mov_b64 s[16:17], -1
	s_sleep 4
	s_cbranch_scc0 .LBB0_296
	s_mov_b64 s[18:19], -1
	s_and_saveexec_b64 s[20:21], s[16:17]
	s_cbranch_execz .LBB0_293
	s_branch .LBB0_299

; __device__ __forceinline__ unsigned xb_ld(unsigned* p)              { return __hip_atomic_load(p, __ATOMIC_RELAXED, __HIP_MEMORY_SCOPE_AGENT); }
; __device__ __forceinline__ void xcd_barrier_complete(unsigned* bar, unsigned x, unsigned& nloc, unsigned& nx) {
;     const unsigned G = gridDim.x * gridDim.y * gridDim.z;
;     unsigned sum, cnt, mine, sp = 0u;
;     for (;;) {
;         sum = 0u; cnt = 0u; mine = 0u;
; #pragma unroll
;         for (unsigned j = 0; j < 16; ++j) { const unsigned c = xb_ld(&bar[XB_XCNT(j)]); sum += c; cnt += (c > 0u) ? 1u : 0u; mine = (j == x) ? c : mine; }
;         if (sum == G) break;
;         __builtin_amdgcn_s_sleep(1);
;         if ((++sp & 255u) == 0u) { if (xb_ld(&bar[XB_TMO])) break; if (sp > XB_SPIN_CAP) { atomicAdd(&bar[XB_TMO], 1u); break; } }
;     }
.LBB0_335:
	v_mov_b64_e32 v[14:15], s[34:35]
	flat_load_dword v12, v[14:15] offset:1024 sc1
	s_waitcnt lgkmcnt(0)
	flat_load_dword v0, v[14:15] offset:1280 sc1
	flat_load_dword v2, v[14:15] offset:1536 sc1
	flat_load_dword v3, v[14:15] offset:1792 sc1
	flat_load_dword v4, v[14:15] offset:2048 sc1
	flat_load_dword v5, v[14:15] offset:2304 sc1
	flat_load_dword v6, v[14:15] offset:2560 sc1
	flat_load_dword v7, v[14:15] offset:2816 sc1
	flat_load_dword v8, v[14:15] offset:3072 sc1
	flat_load_dword v9, v[14:15] offset:3328 sc1
	flat_load_dword v10, v[14:15] offset:3584 sc1
	flat_load_dword v11, v[14:15] offset:3840 sc1
	v_mov_b64_e32 v[14:15], s[0:1]
	flat_load_dword v13, v[14:15] sc1
	v_mov_b64_e32 v[14:15], s[4:5]
	flat_load_dword v14, v[14:15] sc1
	v_mov_b64_e32 v[16:17], s[6:7]
	flat_load_dword v15, v[16:17] sc1
	v_mov_b64_e32 v[16:17], s[8:9]
	flat_load_dword v16, v[16:17] sc1
	v_readlane_b32 s18, v253, 57
	s_or_b64 s[16:17], s[16:17], exec
	s_or_b64 s[14:15], s[14:15], exec
	s_waitcnt vmcnt(0) lgkmcnt(0)
	v_add_u32_e32 v17, v0, v12
	v_add_u32_e32 v17, v17, v2
	v_add_u32_e32 v17, v17, v3
	v_add_u32_e32 v17, v17, v4
	v_add_u32_e32 v17, v17, v5
	v_add_u32_e32 v17, v17, v6
	v_add_u32_e32 v17, v17, v7
	v_add_u32_e32 v17, v17, v8
	v_add_u32_e32 v17, v17, v9
	v_add_u32_e32 v17, v17, v10
	v_add_u32_e32 v17, v17, v11
	v_add_u32_e32 v17, v17, v13
	v_add_u32_e32 v17, v17, v14
	v_add_u32_e32 v17, v17, v15
	v_add_u32_e32 v17, v17, v16
	v_cmp_ne_u32_e32 vcc, s18, v17
	s_and_saveexec_b64 s[18:19], vcc
	s_cbranch_execz .LBB0_334
	s_and_b32 s22, s28, 0xff
	s_mov_b64 s[20:21], -1
	s_cmp_eq_u32 s22, 0
	s_mov_b64 s[24:25], -1
	s_mov_b64 s[22:23], -1
	s_sleep 4
	s_cbranch_scc1 .LBB0_338
	s_and_saveexec_b64 s[26:27], s[24:25]
	s_cbranch_execz .LBB0_333
	s_branch .LBB0_341

; __device__ __forceinline__ unsigned xb_ld(unsigned* p)              { return __hip_atomic_load(p, __ATOMIC_RELAXED, __HIP_MEMORY_SCOPE_AGENT); }
; __device__ __forceinline__ unsigned xb_add(unsigned* p, unsigned v) { return __hip_atomic_fetch_add(p, v, __ATOMIC_RELAXED, __HIP_MEMORY_SCOPE_AGENT); }
; #define XB_SPIN(cond, bar) do { unsigned _sp = 0; while (cond) { __builtin_amdgcn_s_sleep(1); \
;     if ((++_sp & 255u) == 0u) { if (xb_ld(&(bar)[XB_TMO])) break; if (_sp > XB_SPIN_CAP) { atomicAdd(&(bar)[XB_TMO], 1u); break; } } } } while (0)
; __device__ __forceinline__ void xcd_barrier(const XcdBarrier& b) {
;     ...
;             else XB_SPIN(xb_ld(&bar[XB_TOPGEN]) == tg, bar);
;             __builtin_amdgcn_fence(__ATOMIC_ACQUIRE, "agent");
;             xb_add(&bar[XB_XGEN(b.x)], 1u);
;             asm volatile("s_waitcnt vmcnt(0)" ::: "memory");
;         } else {
;             XB_SPIN(xb_ld(&bar[XB_XGEN(b.x)]) == gen, bar);
.LBB0_349:
	s_and_b32 s16, s22, 0xff
	s_mov_b64 s[14:15], -1
	s_cmp_lg_u32 s16, 0
	s_mov_b64 s[16:17], -1
	s_sleep 4
	s_cbranch_scc1 .LBB0_353
	v_mov_b64_e32 v[4:5], s[34:35]
	flat_load_dword v0, v[4:5] offset:512 sc1
	s_mov_b64 s[16:17], 0
	s_mov_b64 s[18:19], -1
	s_waitcnt vmcnt(0) lgkmcnt(0)
	v_cmp_eq_u32_e32 vcc, 0, v0
	s_and_saveexec_b64 s[20:21], vcc
	s_cmp_lt_u32 s22, 0x40001
	s_cselect_b64 s[16:17], -1, 0
	s_xor_b64 s[18:19], exec, -1
	s_and_b64 s[16:17], s[16:17], exec
	s_or_b64 exec, exec, s[20:21]

; __device__ __forceinline__ unsigned xb_ld(unsigned* p)              { return __hip_atomic_load(p, __ATOMIC_RELAXED, __HIP_MEMORY_SCOPE_AGENT); }
; __device__ __forceinline__ unsigned xb_add(unsigned* p, unsigned v) { return __hip_atomic_fetch_add(p, v, __ATOMIC_RELAXED, __HIP_MEMORY_SCOPE_AGENT); }
; #define XB_SPIN(cond, bar) do { unsigned _sp = 0; while (cond) { __builtin_amdgcn_s_sleep(1); \
;     if ((++_sp & 255u) == 0u) { if (xb_ld(&(bar)[XB_TMO])) break; if (_sp > XB_SPIN_CAP) { atomicAdd(&(bar)[XB_TMO], 1u); break; } } } } while (0)
; __device__ __forceinline__ void xcd_barrier(const XcdBarrier& b) {
;     ...
;             else XB_SPIN(xb_ld(&bar[XB_TOPGEN]) == tg, bar);
;             __builtin_amdgcn_fence(__ATOMIC_ACQUIRE, "agent");
;             xb_add(&bar[XB_XGEN(b.x)], 1u);
;             asm volatile("s_waitcnt vmcnt(0)" ::: "memory");
;         } else {
;             XB_SPIN(xb_ld(&bar[XB_XGEN(b.x)]) == gen, bar);
.LBB0_363:
	s_and_b32 s18, s26, 0xff
	s_mov_b64 s[16:17], -1
	s_cmp_lg_u32 s18, 0
	s_mov_b64 s[20:21], -1
	s_sleep 4
	s_cbranch_scc0 .LBB0_365
	s_and_saveexec_b64 s[22:23], s[20:21]
	s_cbranch_execz .LBB0_362
	s_branch .LBB0_368

; __device__ __forceinline__ unsigned xb_ld(unsigned* p)              { return __hip_atomic_load(p, __ATOMIC_RELAXED, __HIP_MEMORY_SCOPE_AGENT); }
; __device__ __forceinline__ void xcd_barrier_complete(unsigned* bar, unsigned x, unsigned& nloc, unsigned& nx) {
;     const unsigned G = gridDim.x * gridDim.y * gridDim.z;
;     unsigned sum, cnt, mine, sp = 0u;
;     for (;;) {
;         sum = 0u; cnt = 0u; mine = 0u;
; #pragma unroll
;         for (unsigned j = 0; j < 16; ++j) { const unsigned c = xb_ld(&bar[XB_XCNT(j)]); sum += c; cnt += (c > 0u) ? 1u : 0u; mine = (j == x) ? c : mine; }
;         if (sum == G) break;
;         __builtin_amdgcn_s_sleep(1);
;         if ((++sp & 255u) == 0u) { if (xb_ld(&bar[XB_TMO])) break; if (sp > XB_SPIN_CAP) { atomicAdd(&bar[XB_TMO], 1u); break; } }
;     }
.LBB0_547:
	v_mov_b64_e32 v[12:13], s[38:39]
	flat_load_dword v2, v[12:13] offset:1024 sc1
	s_waitcnt lgkmcnt(0)
	flat_load_dword v0, v[12:13] offset:1280 sc1
	flat_load_dword v3, v[12:13] offset:1536 sc1
	v_readlane_b32 s16, v253, 57
	s_or_b64 s[14:15], s[14:15], exec
	s_or_b64 s[12:13], s[12:13], exec
	s_waitcnt vmcnt(0) lgkmcnt(0)
	v_add_u32_e32 v4, v0, v2
	v_add_u32_e32 v5, v4, v3
	flat_load_dword v4, v[12:13] offset:1792 sc1
	s_waitcnt vmcnt(0) lgkmcnt(0)
	v_add_u32_e32 v6, v5, v4
	flat_load_dword v5, v[12:13] offset:2048 sc1
	s_waitcnt vmcnt(0) lgkmcnt(0)
	v_add_u32_e32 v7, v6, v5
	flat_load_dword v6, v[12:13] offset:2304 sc1
	s_waitcnt vmcnt(0) lgkmcnt(0)
	v_add_u32_e32 v8, v7, v6
	flat_load_dword v7, v[12:13] offset:2560 sc1
	s_waitcnt vmcnt(0) lgkmcnt(0)
	v_add_u32_e32 v9, v8, v7
	flat_load_dword v8, v[12:13] offset:2816 sc1
	s_waitcnt vmcnt(0) lgkmcnt(0)
	v_add_u32_e32 v10, v9, v8
	flat_load_dword v9, v[12:13] offset:3072 sc1
	s_waitcnt vmcnt(0) lgkmcnt(0)
	v_add_u32_e32 v11, v10, v9
	flat_load_dword v10, v[12:13] offset:3328 sc1
	s_waitcnt vmcnt(0) lgkmcnt(0)
	v_add_u32_e32 v14, v11, v10
	flat_load_dword v11, v[12:13] offset:3584 sc1
	s_waitcnt vmcnt(0) lgkmcnt(0)
	v_add_u32_e32 v14, v14, v11
	flat_load_dword v12, v[12:13] offset:3840 sc1
	s_waitcnt vmcnt(0) lgkmcnt(0)
	v_add_u32_e32 v16, v14, v12
	v_mov_b64_e32 v[14:15], s[0:1]
	flat_load_dword v13, v[14:15] sc1
	v_mov_b64_e32 v[14:15], s[2:3]
	flat_load_dword v14, v[14:15] sc1
	s_waitcnt vmcnt(0) lgkmcnt(0)
	v_add_u32_e32 v16, v16, v13
	v_add_u32_e32 v18, v16, v14
	v_mov_b64_e32 v[16:17], s[4:5]
	flat_load_dword v15, v[16:17] sc1
	v_mov_b64_e32 v[16:17], s[6:7]
	flat_load_dword v16, v[16:17] sc1
	s_waitcnt vmcnt(0) lgkmcnt(0)
	v_add_u32_e32 v18, v18, v15
	v_add_u32_e32 v17, v18, v16
	v_cmp_ne_u32_e32 vcc, s16, v17
	s_and_saveexec_b64 s[16:17], vcc
	s_cbranch_execz .LBB0_546
	s_and_b32 s20, s26, 0xff
	s_mov_b64 s[18:19], -1
	s_cmp_eq_u32 s20, 0
	s_mov_b64 s[22:23], -1
	s_mov_b64 s[20:21], -1
	s_sleep 4
	s_cbranch_scc1 .LBB0_550
	s_and_saveexec_b64 s[24:25], s[22:23]
	s_cbranch_execz .LBB0_545
	s_branch .LBB0_553

; __device__ __forceinline__ unsigned xb_ld(unsigned* p)              { return __hip_atomic_load(p, __ATOMIC_RELAXED, __HIP_MEMORY_SCOPE_AGENT); }
; __device__ __forceinline__ unsigned xb_add(unsigned* p, unsigned v) { return __hip_atomic_fetch_add(p, v, __ATOMIC_RELAXED, __HIP_MEMORY_SCOPE_AGENT); }
; #define XB_SPIN(cond, bar) do { unsigned _sp = 0; while (cond) { __builtin_amdgcn_s_sleep(1); \
;     if ((++_sp & 255u) == 0u) { if (xb_ld(&(bar)[XB_TMO])) break; if (_sp > XB_SPIN_CAP) { atomicAdd(&(bar)[XB_TMO], 1u); break; } } } } while (0)
; __device__ __forceinline__ void xcd_barrier(const XcdBarrier& b) {
;     ...
;             else XB_SPIN(xb_ld(&bar[XB_TOPGEN]) == tg, bar);
;             __builtin_amdgcn_fence(__ATOMIC_ACQUIRE, "agent");
;             xb_add(&bar[XB_XGEN(b.x)], 1u);
;             asm volatile("s_waitcnt vmcnt(0)" ::: "memory");
;         } else {
;             XB_SPIN(xb_ld(&bar[XB_XGEN(b.x)]) == gen, bar);
.LBB0_561:
	s_and_b32 s14, s22, 0xff
	s_mov_b64 s[12:13], -1
	s_cmp_lg_u32 s14, 0
	s_mov_b64 s[14:15], -1
	s_sleep 4
	s_cbranch_scc1 .LBB0_565
	v_mov_b64_e32 v[4:5], s[38:39]
	flat_load_dword v0, v[4:5] offset:512 sc1
	s_mov_b64 s[14:15], 0
	s_mov_b64 s[16:17], -1
	s_waitcnt vmcnt(0) lgkmcnt(0)
	v_cmp_eq_u32_e32 vcc, 0, v0
	s_and_saveexec_b64 s[18:19], vcc
	s_cmp_lt_u32 s22, 0x40001
	s_cselect_b64 s[14:15], -1, 0
	s_xor_b64 s[16:17], exec, -1
	s_and_b64 s[14:15], s[14:15], exec
	s_or_b64 exec, exec, s[18:19]

; __device__ __forceinline__ unsigned xb_ld(unsigned* p)              { return __hip_atomic_load(p, __ATOMIC_RELAXED, __HIP_MEMORY_SCOPE_AGENT); }
; __device__ __forceinline__ unsigned xb_add(unsigned* p, unsigned v) { return __hip_atomic_fetch_add(p, v, __ATOMIC_RELAXED, __HIP_MEMORY_SCOPE_AGENT); }
; #define XB_SPIN(cond, bar) do { unsigned _sp = 0; while (cond) { __builtin_amdgcn_s_sleep(1); \
;     if ((++_sp & 255u) == 0u) { if (xb_ld(&(bar)[XB_TMO])) break; if (_sp > XB_SPIN_CAP) { atomicAdd(&(bar)[XB_TMO], 1u); break; } } } } while (0)
; __device__ __forceinline__ void xcd_barrier(const XcdBarrier& b) {
;     ...
;             else XB_SPIN(xb_ld(&bar[XB_TOPGEN]) == tg, bar);
;             __builtin_amdgcn_fence(__ATOMIC_ACQUIRE, "agent");
;             xb_add(&bar[XB_XGEN(b.x)], 1u);
;             asm volatile("s_waitcnt vmcnt(0)" ::: "memory");
;         } else {
;             XB_SPIN(xb_ld(&bar[XB_XGEN(b.x)]) == gen, bar);
.LBB0_575:
	s_and_b32 s14, s22, 0xff
	s_mov_b64 s[12:13], -1
	s_cmp_lg_u32 s14, 0
	s_mov_b64 s[16:17], -1
	s_sleep 4
	s_cbranch_scc0 .LBB0_577
	s_and_saveexec_b64 s[18:19], s[16:17]
	s_cbranch_execz .LBB0_574
	s_branch .LBB0_580

; __device__ __forceinline__ unsigned xb_ld(unsigned* p)              { return __hip_atomic_load(p, __ATOMIC_RELAXED, __HIP_MEMORY_SCOPE_AGENT); }
; __device__ __forceinline__ unsigned xb_add(unsigned* p, unsigned v) { return __hip_atomic_fetch_add(p, v, __ATOMIC_RELAXED, __HIP_MEMORY_SCOPE_AGENT); }
; #define XB_SPIN(cond, bar) do { unsigned _sp = 0; while (cond) { __builtin_amdgcn_s_sleep(1); \
;     if ((++_sp & 255u) == 0u) { if (xb_ld(&(bar)[XB_TMO])) break; if (_sp > XB_SPIN_CAP) { atomicAdd(&(bar)[XB_TMO], 1u); break; } } } } while (0)
; __device__ __forceinline__ void xcd_barrier(const XcdBarrier& b) {
;     ...
;             else XB_SPIN(xb_ld(&bar[XB_TOPGEN]) == tg, bar);
;             __builtin_amdgcn_fence(__ATOMIC_ACQUIRE, "agent");
;             xb_add(&bar[XB_XGEN(b.x)], 1u);
;             asm volatile("s_waitcnt vmcnt(0)" ::: "memory");
;         } else {
;             XB_SPIN(xb_ld(&bar[XB_XGEN(b.x)]) == gen, bar);
.LBB0_610:
	s_and_b32 s14, s20, 0xff
	s_mov_b64 s[12:13], -1
	s_cmp_lg_u32 s14, 0
	s_mov_b64 s[14:15], -1
	s_sleep 4
	s_cbranch_scc1 .LBB0_614
	v_mov_b64_e32 v[4:5], s[38:39]
	flat_load_dword v0, v[4:5] offset:512 sc1
	s_mov_b64 s[14:15], 0
	s_mov_b64 s[16:17], -1
	s_waitcnt vmcnt(0) lgkmcnt(0)
	v_cmp_eq_u32_e32 vcc, 0, v0
	s_and_saveexec_b64 s[18:19], vcc
	s_cmp_lt_u32 s20, 0x40001
	s_cselect_b64 s[14:15], -1, 0
	s_xor_b64 s[16:17], exec, -1
	s_and_b64 s[14:15], s[14:15], exec
	s_or_b64 exec, exec, s[18:19]

; __device__ __forceinline__ unsigned xb_ld(unsigned* p)              { return __hip_atomic_load(p, __ATOMIC_RELAXED, __HIP_MEMORY_SCOPE_AGENT); }
; __device__ __forceinline__ unsigned xb_add(unsigned* p, unsigned v) { return __hip_atomic_fetch_add(p, v, __ATOMIC_RELAXED, __HIP_MEMORY_SCOPE_AGENT); }
; #define XB_SPIN(cond, bar) do { unsigned _sp = 0; while (cond) { __builtin_amdgcn_s_sleep(1); \
;     if ((++_sp & 255u) == 0u) { if (xb_ld(&(bar)[XB_TMO])) break; if (_sp > XB_SPIN_CAP) { atomicAdd(&(bar)[XB_TMO], 1u); break; } } } } while (0)
; __device__ __forceinline__ void xcd_barrier(const XcdBarrier& b) {
;     ...
;             else XB_SPIN(xb_ld(&bar[XB_TOPGEN]) == tg, bar);
;             __builtin_amdgcn_fence(__ATOMIC_ACQUIRE, "agent");
;             xb_add(&bar[XB_XGEN(b.x)], 1u);
;             asm volatile("s_waitcnt vmcnt(0)" ::: "memory");
;         } else {
;             XB_SPIN(xb_ld(&bar[XB_XGEN(b.x)]) == gen, bar);
.LBB0_624:
	s_and_b32 s16, s24, 0xff
	s_mov_b64 s[14:15], -1
	s_cmp_lg_u32 s16, 0
	s_mov_b64 s[18:19], -1
	s_sleep 4
	s_cbranch_scc0 .LBB0_626
	s_and_saveexec_b64 s[20:21], s[18:19]
	s_cbranch_execz .LBB0_623
	s_branch .LBB0_629

; __device__ __forceinline__ unsigned xb_ld(unsigned* p)              { return __hip_atomic_load(p, __ATOMIC_RELAXED, __HIP_MEMORY_SCOPE_AGENT); }
; __device__ __forceinline__ void xcd_barrier_complete(unsigned* bar, unsigned x, unsigned& nloc, unsigned& nx) {
;     const unsigned G = gridDim.x * gridDim.y * gridDim.z;
;     unsigned sum, cnt, mine, sp = 0u;
;     for (;;) {
;         sum = 0u; cnt = 0u; mine = 0u;
; #pragma unroll
;         for (unsigned j = 0; j < 16; ++j) { const unsigned c = xb_ld(&bar[XB_XCNT(j)]); sum += c; cnt += (c > 0u) ? 1u : 0u; mine = (j == x) ? c : mine; }
;         if (sum == G) break;
;         __builtin_amdgcn_s_sleep(1);
;         if ((++sp & 255u) == 0u) { if (xb_ld(&bar[XB_TMO])) break; if (sp > XB_SPIN_CAP) { atomicAdd(&bar[XB_TMO], 1u); break; } }
;     }
.LBB0_1101:
	v_mov_b64_e32 v[12:13], s[36:37]
	flat_load_dword v2, v[12:13] offset:1024 sc1
	s_waitcnt lgkmcnt(0)
	flat_load_dword v0, v[12:13] offset:1280 sc1
	flat_load_dword v3, v[12:13] offset:1536 sc1
	v_readlane_b32 s16, v253, 57
	s_or_b64 s[14:15], s[14:15], exec
	s_or_b64 s[12:13], s[12:13], exec
	s_waitcnt vmcnt(0) lgkmcnt(0)
	v_add_u32_e32 v4, v0, v2
	v_add_u32_e32 v5, v4, v3
	flat_load_dword v4, v[12:13] offset:1792 sc1
	s_waitcnt vmcnt(0) lgkmcnt(0)
	v_add_u32_e32 v6, v5, v4
	flat_load_dword v5, v[12:13] offset:2048 sc1
	s_waitcnt vmcnt(0) lgkmcnt(0)
	v_add_u32_e32 v7, v6, v5
	flat_load_dword v6, v[12:13] offset:2304 sc1
	s_waitcnt vmcnt(0) lgkmcnt(0)
	v_add_u32_e32 v8, v7, v6
	flat_load_dword v7, v[12:13] offset:2560 sc1
	s_waitcnt vmcnt(0) lgkmcnt(0)
	v_add_u32_e32 v9, v8, v7
	flat_load_dword v8, v[12:13] offset:2816 sc1
	s_waitcnt vmcnt(0) lgkmcnt(0)
	v_add_u32_e32 v10, v9, v8
	flat_load_dword v9, v[12:13] offset:3072 sc1
	s_waitcnt vmcnt(0) lgkmcnt(0)
	v_add_u32_e32 v11, v10, v9
	flat_load_dword v10, v[12:13] offset:3328 sc1
	s_waitcnt vmcnt(0) lgkmcnt(0)
	v_add_u32_e32 v14, v11, v10
	flat_load_dword v11, v[12:13] offset:3584 sc1
	s_waitcnt vmcnt(0) lgkmcnt(0)
	v_add_u32_e32 v14, v14, v11
	flat_load_dword v12, v[12:13] offset:3840 sc1
	s_waitcnt vmcnt(0) lgkmcnt(0)
	v_add_u32_e32 v16, v14, v12
	v_mov_b64_e32 v[14:15], s[0:1]
	flat_load_dword v13, v[14:15] sc1
	v_mov_b64_e32 v[14:15], s[2:3]
	flat_load_dword v14, v[14:15] sc1
	s_waitcnt vmcnt(0) lgkmcnt(0)
	v_add_u32_e32 v16, v16, v13
	v_add_u32_e32 v18, v16, v14
	v_mov_b64_e32 v[16:17], s[4:5]
	flat_load_dword v15, v[16:17] sc1
	v_mov_b64_e32 v[16:17], s[6:7]
	flat_load_dword v16, v[16:17] sc1
	s_waitcnt vmcnt(0) lgkmcnt(0)
	v_add_u32_e32 v18, v18, v15
	v_add_u32_e32 v17, v18, v16
	v_cmp_ne_u32_e32 vcc, s16, v17
	s_and_saveexec_b64 s[16:17], vcc
	s_cbranch_execz .LBB0_1100
	s_and_b32 s20, s26, 0xff
	s_mov_b64 s[18:19], -1
	s_cmp_eq_u32 s20, 0
	s_mov_b64 s[22:23], -1
	s_mov_b64 s[20:21], -1
	s_sleep 4
	s_cbranch_scc1 .LBB0_1104
	s_and_saveexec_b64 s[24:25], s[22:23]
	s_cbranch_execz .LBB0_1099
	s_branch .LBB0_1107

; __device__ __forceinline__ unsigned xb_ld(unsigned* p)              { return __hip_atomic_load(p, __ATOMIC_RELAXED, __HIP_MEMORY_SCOPE_AGENT); }
; __device__ __forceinline__ unsigned xb_add(unsigned* p, unsigned v) { return __hip_atomic_fetch_add(p, v, __ATOMIC_RELAXED, __HIP_MEMORY_SCOPE_AGENT); }
; #define XB_SPIN(cond, bar) do { unsigned _sp = 0; while (cond) { __builtin_amdgcn_s_sleep(1); \
;     if ((++_sp & 255u) == 0u) { if (xb_ld(&(bar)[XB_TMO])) break; if (_sp > XB_SPIN_CAP) { atomicAdd(&(bar)[XB_TMO], 1u); break; } } } } while (0)
; __device__ __forceinline__ void xcd_barrier(const XcdBarrier& b) {
;     ...
;             else XB_SPIN(xb_ld(&bar[XB_TOPGEN]) == tg, bar);
;             __builtin_amdgcn_fence(__ATOMIC_ACQUIRE, "agent");
;             xb_add(&bar[XB_XGEN(b.x)], 1u);
;             asm volatile("s_waitcnt vmcnt(0)" ::: "memory");
;         } else {
;             XB_SPIN(xb_ld(&bar[XB_XGEN(b.x)]) == gen, bar);
.LBB0_1115:
	s_and_b32 s14, s22, 0xff
	s_mov_b64 s[12:13], -1
	s_cmp_lg_u32 s14, 0
	s_mov_b64 s[14:15], -1
	s_sleep 4
	s_cbranch_scc1 .LBB0_1119
	v_mov_b64_e32 v[4:5], s[36:37]
	flat_load_dword v0, v[4:5] offset:512 sc1
	s_mov_b64 s[14:15], 0
	s_mov_b64 s[16:17], -1
	s_waitcnt vmcnt(0) lgkmcnt(0)
	v_cmp_eq_u32_e32 vcc, 0, v0
	s_and_saveexec_b64 s[18:19], vcc
	s_cmp_lt_u32 s22, 0x40001
	s_cselect_b64 s[14:15], -1, 0
	s_xor_b64 s[16:17], exec, -1
	s_and_b64 s[14:15], s[14:15], exec
	s_or_b64 exec, exec, s[18:19]

; __device__ __forceinline__ unsigned xb_ld(unsigned* p)              { return __hip_atomic_load(p, __ATOMIC_RELAXED, __HIP_MEMORY_SCOPE_AGENT); }
; __device__ __forceinline__ unsigned xb_add(unsigned* p, unsigned v) { return __hip_atomic_fetch_add(p, v, __ATOMIC_RELAXED, __HIP_MEMORY_SCOPE_AGENT); }
; #define XB_SPIN(cond, bar) do { unsigned _sp = 0; while (cond) { __builtin_amdgcn_s_sleep(1); \
;     if ((++_sp & 255u) == 0u) { if (xb_ld(&(bar)[XB_TMO])) break; if (_sp > XB_SPIN_CAP) { atomicAdd(&(bar)[XB_TMO], 1u); break; } } } } while (0)
; __device__ __forceinline__ void xcd_barrier(const XcdBarrier& b) {
;     ...
;             else XB_SPIN(xb_ld(&bar[XB_TOPGEN]) == tg, bar);
;             __builtin_amdgcn_fence(__ATOMIC_ACQUIRE, "agent");
;             xb_add(&bar[XB_XGEN(b.x)], 1u);
;             asm volatile("s_waitcnt vmcnt(0)" ::: "memory");
;         } else {
;             XB_SPIN(xb_ld(&bar[XB_XGEN(b.x)]) == gen, bar);
.LBB0_1372:
	s_and_b32 s14, s20, 0xff
	s_mov_b64 s[12:13], -1
	s_cmp_lg_u32 s14, 0
	s_mov_b64 s[14:15], -1
	s_sleep 4
	s_cbranch_scc1 .LBB0_1376
	v_mov_b64_e32 v[4:5], s[36:37]
	flat_load_dword v0, v[4:5] offset:512 sc1
	s_mov_b64 s[14:15], 0
	s_mov_b64 s[16:17], -1
	s_waitcnt vmcnt(0) lgkmcnt(0)
	v_cmp_eq_u32_e32 vcc, 0, v0
	s_and_saveexec_b64 s[18:19], vcc
	s_cmp_lt_u32 s20, 0x40001
	s_cselect_b64 s[14:15], -1, 0
	s_xor_b64 s[16:17], exec, -1
	s_and_b64 s[14:15], s[14:15], exec
	s_or_b64 exec, exec, s[18:19]
